# P6 tail round: the 96 leftover units run as 192 half-tiles (M-split by accumulator half) on 192 workgroups instead of 96 whole tiles
# baseline (speedup 1.0000x reference)
; #define PG8_STAGE(bufoff, gbase, voff) do { const char* _gb = (const char*)(gbase); asm volatile("" : "+s"(_gb));     \
;         _Pragma("unroll") for (int _i = 0; _i < 2; ++_i) \
;         __builtin_amdgcn_global_load_lds((const unsigned*)(_gb + (voff)[_i]), (LAS unsigned*)(lds + (bufoff) + ldsw + _i * 8192), 16, 0, 0); } while (0)
; #define PG8_VOFF_OPAQUE asm volatile("" : "+v"(voffA[0]), "+v"(voffA[1]), "+v"(voffB[0]), "+v"(voffB[1]))
; #define PG8_WAIT_V(n) asm volatile("s_waitcnt vmcnt(" #n ")" ::: "memory")
; #define PG8_BAR __builtin_amdgcn_s_barrier()
; template <class Epi>
; __device__ __forceinline__ void gemm_phase(LAS unsigned char* lds, const Gemm g, const StaticOrder& S, const Epi& E) {
;     ...
;     const char* cA = (const char*)gA + (size_t)cur.pm * tstepA + (size_t)cur.pn * acolb + (size_t)cur.kofs * kstepA; const char* cB = (const char*)gB + (size_t)cur.pn * tstepB + (size_t)cur.kofs * kstepB;
;     PG8_VOFF_OPAQUE;
;     PG8_STAGE(PG8_SB(0, 0), cB, voffB); PG8_STAGE(PG8_SB(0, 1), cB + hstepB, voffB); PG8_STAGE(PG8_SA(0, 0), cA, voffA); PG8_STAGE(PG8_SA(0, 1), cA + hstepA, voffA);
;     if (wr == 1) PG8_BAR;
;     PG8_WAIT_V(2); PG8_BAR;
;     PG8_STAGE(PG8_SB(1, 0), cB + kstepB, voffB); PG8_STAGE(PG8_SA(1, 0), cA + kstepA, voffA); PG8_STAGE(PG8_SB(1, 1), cB + hstepB + kstepB, voffB);
;     PG8_WAIT_V(6); PG8_BAR;
.LBB0_1199:
	s_add_u32 s36, s8, 0xe10c000
	s_addc_u32 s37, s9, 0
	s_add_u32 s38, s8, 0x24000
	s_addc_u32 s39, s9, 0
	s_lshl_b32 s44, s27, 5
	s_and_b32 s27, s44, 0x60
	s_lshl_b32 s26, s33, 6
	s_lshl_b32 s11, s33, 13
	s_lshl_b32 s45, s27, 7
	s_add_u32 s8, s52, 0x80
	s_addc_u32 s9, s53, 0
	s_waitcnt vmcnt(2)
	s_barrier
	s_add_i32 m0, s6, 0x18000
	v_lshl_add_u64 v[2:3], s[8:9], 0, v[132:133]
	global_load_lds_dwordx4 v[2:3], off
	s_add_i32 m0, s6, 0x1a000
	v_lshl_add_u64 v[2:3], s[8:9], 0, v[128:129]
	s_add_u32 s8, s54, 0x80
	s_addc_u32 s9, s55, 0
	s_add_i32 s33, s6, 0x8000
	global_load_lds_dwordx4 v[2:3], off
	s_mov_b32 m0, s33
	v_lshl_add_u64 v[2:3], s[8:9], 0, v[134:135]
	s_add_i32 s43, s6, 0xa000
	global_load_lds_dwordx4 v[2:3], off
	v_lshl_add_u64 v[2:3], s[8:9], 0, v[130:131]
	s_add_u32 s8, s40, 0x80
	s_mov_b32 m0, s43
	s_addc_u32 s9, s41, 0
	global_load_lds_dwordx4 v[2:3], off
	s_add_i32 m0, s6, 0x1c000
	v_lshl_add_u64 v[2:3], s[8:9], 0, v[132:133]
	global_load_lds_dwordx4 v[2:3], off
	v_lshl_add_u64 v[2:3], s[8:9], 0, v[128:129]
	s_add_i32 m0, s6, 0x1e000
	v_lshrrev_b32_e32 v1, 1, v0
	global_load_lds_dwordx4 v[2:3], off
	s_waitcnt vmcnt(6)
	s_barrier
	s_load_dwordx2 s[8:9], s[0:1], 0xb8
	v_and_b32_e32 v1, 24, v1
	v_and_b32_e32 v129, 15, v0
	v_lshlrev_b32_e32 v2, 1, v1
	v_lshlrev_b32_e32 v0, 2, v0
	v_lshl_or_b32 v2, v129, 6, v2
	v_and_b32_e32 v0, 32, v0
	s_cmpk_lt_u32 s42, 0x100
	v_bitop3_b32 v3, v2, s11, v0 bitop3:0xde
	v_bitop3_b32 v131, v2, s45, v0 bitop3:0xde
	s_cselect_b64 s[40:41], -1, 0
	v_and_or_b32 v0, s44, 32, v1
	s_add_i32 s59, 0, 0x10000
	s_add_i32 s60, 0, 0x14000
	s_sext_i32_i16 s63, s10
	s_waitcnt lgkmcnt(0)
	s_ashr_i32 s51, s8, 31
	s_mov_b32 s58, s8
	v_mov_b64_e32 v[136:137], 0xc60
	v_mov_b64_e32 v[138:139], 0xc5f
	v_add_u32_e32 v135, s59, v131
	v_add_u32_e32 v143, s60, v131
	v_add_u32_e32 v145, 0, v3
	v_mov_b32_e32 v147, 0x358637bd
	s_mov_b32 s42, 0xbfb8aa3b
	v_lshlrev_b32_e32 v140, 1, v0
	s_movk_i32 s61, 0x1000
	v_mov_b32_e32 v149, v132
	s_mov_b32 s94, 0
	s_mov_b32 s95, 0
	s_branch .LBB0_1202

;     __host__ __device__ bool next(int i, Unit& u) const {
;         u.kofs = 0; u.nt = ntf; u.part = -1;
;         if (split && i >= 2) {
;             if (i > 2) return false;
;             const int x = c % NXCD, ci = c / NXCD;
;             tile(x * (nwg / NXCD) + 64 + (ci >> 2), u); u.nt = ntf / 4; u.kofs = (ci & 3) * u.nt; u.part = c; return true;
;         }
;         const long L = (long)i * G + c; if (L >= nwg) return false;
;         int wgid = (int)L; { const int q = nwg / NXCD, r = nwg % NXCD, xcd = wgid % NXCD, off = wgid / NXCD; wgid = (xcd < r ? xcd * (q + 1) : r * (q + 1) + (xcd - r) * q) + off; }
;         tile(wgid, u); return true;
.LBB0_1201:
	s_andn2_b64 vcc, exec, s[8:9]
	s_mov_b32 s63, s62
	s_mov_b32 s50, s44
	s_mov_b64 s[54:55], s[48:49]
	s_mov_b64 s[52:53], s[46:47]
	s_mov_b32 s94, s95
	s_cbranch_vccz .LBB0_1213
.LBB0_1202:
	s_add_i32 s25, s25, 1
	s_mul_i32 s8, s25, s51
	s_mul_hi_u32 s9, s25, s58
	s_add_i32 s9, s9, s8
	s_mul_i32 s8, s25, s58
	s_add_u32 s8, s8, s2
	s_addc_u32 s9, s9, s4
	s_mov_b32 s95, 0
	s_cmp_lg_u32 s58, 0x100
	s_cbranch_scc1 .Lp6_sched_done
	s_cmp_lg_u32 s25, 12
	s_cbranch_scc1 .Lp6_sched_done
	s_lshr_b32 s96, s2, 4
	s_lshl_b32 s96, s96, 3
	s_and_b32 s97, s2, 7
	s_add_u32 s8, s96, s97
	s_add_u32 s8, s8, 0xc00
	s_mov_b32 s9, 0
	s_bfe_u32 s95, s2, 0x10003
	s_add_u32 s95, s95, 1
	s_cmp_lt_u32 s2, 0xc0
	s_cbranch_scc1 .Lp6_sched_done
	s_mov_b32 s8, 0xc60
	s_mov_b32 s95, 0
.Lp6_sched_done:
	v_cmp_gt_i64_e32 vcc, s[8:9], v[138:139]
	v_cmp_lt_i64_e64 s[10:11], s[8:9], v[136:137]
	s_cbranch_vccnz .LBB0_1204
	s_ashr_i32 s9, s8, 31
	s_lshr_b32 s9, s9, 29
	s_add_i32 s9, s8, s9
	s_ashr_i32 s44, s9, 3
	s_and_b32 s9, s9, -8
	s_sub_i32 s8, s8, s9
	s_cmp_lt_i32 s8, 0
	s_cselect_b32 s9, s5, 0x18c
	s_mul_i32 s8, s9, s8
	s_add_i32 s8, s8, s44
	s_mul_hi_i32 s9, s8, 0x2e8ba2e9
	s_lshr_b32 s44, s9, 31
	s_ashr_i32 s9, s9, 5
	s_add_i32 s9, s9, s44
	s_lshl_b32 s44, s9, 2
	s_sub_i32 s45, 0x48, s44
	s_min_i32 s45, s45, 4
	s_abs_i32 s46, s45
	v_cvt_f32_u32_e32 v0, s46
	s_sub_i32 s48, 0, s46
	s_mulk_i32 s9, 0xb0
	s_sub_i32 s8, s8, s9
	v_rcp_iflag_f32_e32 v0, v0
	s_abs_i32 s9, s8
	s_xor_b32 s47, s8, s45
	s_ashr_i32 s47, s47, 31
	v_mul_f32_e32 v0, 0x4f7ffffe, v0
	v_cvt_u32_f32_e32 v0, v0
	s_nop 0
	v_readfirstlane_b32 s49, v0
	s_mul_i32 s48, s48, s49
	s_mul_hi_u32 s48, s49, s48
	s_add_i32 s49, s49, s48
	s_mul_hi_u32 s48, s9, s49
	s_mul_i32 s49, s48, s46
	s_sub_i32 s9, s9, s49
	s_add_i32 s56, s48, 1
	s_sub_i32 s49, s9, s46
	s_cmp_ge_u32 s9, s46
	s_cselect_b32 s48, s56, s48
	s_cselect_b32 s9, s49, s9
	s_add_i32 s49, s48, 1
	s_cmp_ge_u32 s9, s46
	s_cselect_b32 s9, s49, s48
	s_xor_b32 s9, s9, s47
	s_sub_i32 s62, s9, s47
	s_mul_i32 s9, s62, s45
	s_sub_i32 s8, s8, s9
	s_add_i32 s44, s8, s44

; #define PG8_STAGE(bufoff, gbase, voff) do { const char* _gb = (const char*)(gbase); asm volatile("" : "+s"(_gb));     \
;         _Pragma("unroll") for (int _i = 0; _i < 2; ++_i) \
;         __builtin_amdgcn_global_load_lds((const unsigned*)(_gb + (voff)[_i]), (LAS unsigned*)(lds + (bufoff) + ldsw + _i * 8192), 16, 0, 0); } while (0)
; #define PG8_LDA(dst, b, h) do { _Pragma("unroll") for (int m = 0; m < 4; ++m) _Pragma("unroll") for (int k = 0; k < 2; ++k) dst[m][k] = *(const LAS bf16x8*)(lds + PG8_SA(b, h) + aoff + m * 2048 + k * 1024); } while (0)
; #define PG8_LDB(dst, b, h) do { _Pragma("unroll") for (int n = 0; n < 2; ++n) _Pragma("unroll") for (int k = 0; k < 2; ++k) dst[n][k] = *(const LAS bf16x8*)(lds + PG8_SB(b, h) + boff + n * 2048 + k * 1024); } while (0)
; #define PG8_WAIT_V(n) asm volatile("s_waitcnt vmcnt(" #n ")" ::: "memory")
; #define PG8_WAIT_L(n) asm volatile("s_waitcnt lgkmcnt(" #n ")" ::: "memory")
; #define PG8_BAR __builtin_amdgcn_s_barrier()
; #define PG8_SCHED __builtin_amdgcn_sched_barrier(0)
; template <class Epi>
; __device__ __forceinline__ void gemm_phase(LAS unsigned char* lds, const Gemm g, const StaticOrder& S, const Epi& E) {
;     ...
;             PG8_LDB(B0, 0, 0); PG8_LDB(B1, 0, 1); PG8_SCHED; PG8_LDA(At, 0, 0); PG8_STAGE(PG8_SA(1, 1), a1 + hstepA, voffA);
;             PG8_WAIT_V(8); PG8_WAIT_L(0); PG8_BAR; PG8_MMA2(0, At, B0, B1); PG8_BAR; PG8_SCHED;
;             PG8_LDA(At, 0, 1); PG8_STAGE(PG8_SB(0, 0), b2, voffB); PG8_STAGE(PG8_SB(0, 1), b2 + hstepB, voffB); PG8_STAGE(PG8_SA(0, 0), a2, voffA);
;             PG8_WAIT_V(8); PG8_WAIT_L(0); PG8_BAR; PG8_MMA2(1, At, B0, B1); PG8_BAR; PG8_SCHED;
.LBB0_1207:
	ds_read_b128 v[150:153], v135
	ds_read_b128 v[154:157], v135 offset:1024
	ds_read_b128 v[158:161], v135 offset:2048
	ds_read_b128 v[162:165], v135 offset:3072
	ds_read_b128 v[166:169], v143
	ds_read_b128 v[170:173], v143 offset:1024
	ds_read_b128 v[174:177], v143 offset:2048
	ds_read_b128 v[178:181], v143 offset:3072
	s_cmp_eq_u32 s69, 28
	s_cselect_b32 s54, s64, s67
	s_cselect_b32 s55, s45, s68
	s_cselect_b32 s52, s46, s65
	s_cselect_b32 s53, s47, s66
	s_add_u32 s10, s54, 0x80
	s_addc_u32 s11, s55, 0
	s_add_u32 s56, s67, s22
	s_addc_u32 s57, s68, s23
	s_add_u32 s56, s56, 0xffffff80
	s_addc_u32 s57, s57, -1
	s_add_i32 m0, s6, 0xc000
	ds_read_b128 v[182:185], v145
	ds_read_b128 v[186:189], v145 offset:1024
	ds_read_b128 v[190:193], v145 offset:2048
	ds_read_b128 v[194:197], v145 offset:3072
	ds_read_b128 v[198:201], v145 offset:4096
	ds_read_b128 v[202:205], v145 offset:5120
	ds_read_b128 v[206:209], v145 offset:6144
	ds_read_b128 v[210:213], v145 offset:7168
	s_nop 0
	global_load_lds_dwordx4 v134, s[56:57]
	s_add_i32 m0, s6, 0xe000
	s_nop 0
	global_load_lds_dwordx4 v130, s[56:57]
	s_waitcnt vmcnt(8)
	s_waitcnt lgkmcnt(0)
	s_barrier
	s_cmp_eq_u32 s94, 2
	s_cbranch_scc1 .Lp6_skipm1
	s_setprio 1
	s_waitcnt lgkmcnt(0)
	v_mfma_f32_16x16x32_bf16 v[124:127], v[150:153], v[182:185], v[124:127]
	v_mfma_f32_16x16x32_bf16 v[120:123], v[158:161], v[182:185], v[120:123]
	v_mfma_f32_16x16x32_bf16 v[108:111], v[150:153], v[190:193], v[108:111]
	v_mfma_f32_16x16x32_bf16 v[104:107], v[158:161], v[190:193], v[104:107]
	v_mfma_f32_16x16x32_bf16 v[92:95], v[150:153], v[198:201], v[92:95]
	v_mfma_f32_16x16x32_bf16 v[88:91], v[158:161], v[198:201], v[88:91]
	v_mfma_f32_16x16x32_bf16 v[76:79], v[150:153], v[206:209], v[76:79]
	v_mfma_f32_16x16x32_bf16 v[72:75], v[158:161], v[206:209], v[72:75]
	v_mfma_f32_16x16x32_bf16 v[116:119], v[166:169], v[182:185], v[116:119]
	v_mfma_f32_16x16x32_bf16 v[112:115], v[174:177], v[182:185], v[112:115]
	v_mfma_f32_16x16x32_bf16 v[100:103], v[166:169], v[190:193], v[100:103]
	v_mfma_f32_16x16x32_bf16 v[96:99], v[174:177], v[190:193], v[96:99]
	v_mfma_f32_16x16x32_bf16 v[84:87], v[166:169], v[198:201], v[84:87]
	v_mfma_f32_16x16x32_bf16 v[80:83], v[174:177], v[198:201], v[80:83]
	v_mfma_f32_16x16x32_bf16 v[68:71], v[166:169], v[206:209], v[68:71]
	v_mfma_f32_16x16x32_bf16 v[64:67], v[174:177], v[206:209], v[64:67]
	v_mfma_f32_16x16x32_bf16 v[124:127], v[154:157], v[186:189], v[124:127]
	v_mfma_f32_16x16x32_bf16 v[120:123], v[162:165], v[186:189], v[120:123]
	v_mfma_f32_16x16x32_bf16 v[108:111], v[154:157], v[194:197], v[108:111]
	v_mfma_f32_16x16x32_bf16 v[104:107], v[162:165], v[194:197], v[104:107]
	v_mfma_f32_16x16x32_bf16 v[92:95], v[154:157], v[202:205], v[92:95]
	v_mfma_f32_16x16x32_bf16 v[88:91], v[162:165], v[202:205], v[88:91]
	v_mfma_f32_16x16x32_bf16 v[76:79], v[154:157], v[210:213], v[76:79]
	v_mfma_f32_16x16x32_bf16 v[72:75], v[162:165], v[210:213], v[72:75]
	v_mfma_f32_16x16x32_bf16 v[116:119], v[170:173], v[186:189], v[116:119]
	v_mfma_f32_16x16x32_bf16 v[112:115], v[178:181], v[186:189], v[112:115]
	v_mfma_f32_16x16x32_bf16 v[100:103], v[170:173], v[194:197], v[100:103]
	v_mfma_f32_16x16x32_bf16 v[96:99], v[178:181], v[194:197], v[96:99]
	v_mfma_f32_16x16x32_bf16 v[84:87], v[170:173], v[202:205], v[84:87]
	v_mfma_f32_16x16x32_bf16 v[80:83], v[178:181], v[202:205], v[80:83]
	v_mfma_f32_16x16x32_bf16 v[68:71], v[170:173], v[210:213], v[68:71]
	v_mfma_f32_16x16x32_bf16 v[64:67], v[178:181], v[210:213], v[64:67]
	s_setprio 0
.Lp6_skipm1:
	s_barrier
	s_add_i32 s70, s59, s3
	s_mov_b64 s[56:57], s[52:53]
	s_mov_b32 m0, s70
	ds_read_b128 v[182:185], v145 offset:16384
	ds_read_b128 v[186:189], v145 offset:17408
	ds_read_b128 v[190:193], v145 offset:18432
	ds_read_b128 v[194:197], v145 offset:19456
	ds_read_b128 v[198:201], v145 offset:20480
	ds_read_b128 v[202:205], v145 offset:21504
	ds_read_b128 v[206:209], v145 offset:22528
	ds_read_b128 v[210:213], v145 offset:23552
	s_nop 0
	global_load_lds_dwordx4 v149, s[56:57]
	s_add_i32 m0, s70, 0x2000
	s_nop 0
	global_load_lds_dwordx4 v128, s[56:57]
	s_add_u32 s56, s52, s16
	s_addc_u32 s57, s53, s17
	s_add_i32 s72, s60, s3
	s_mov_b64 s[70:71], s[56:57]
	s_mov_b32 m0, s72
	s_nop 0
	global_load_lds_dwordx4 v149, s[70:71]
	s_add_i32 m0, s72, 0x2000
	s_nop 0
	global_load_lds_dwordx4 v128, s[70:71]
	s_mov_b64 s[70:71], s[54:55]
	s_mov_b32 m0, s6
	s_nop 0
	global_load_lds_dwordx4 v134, s[70:71]
	s_mov_b32 m0, s7
	s_nop 0
	global_load_lds_dwordx4 v130, s[70:71]
	s_waitcnt vmcnt(8)
	s_waitcnt lgkmcnt(0)
	s_barrier
	s_cmp_eq_u32 s94, 1
	s_cbranch_scc1 .Lp6_skipm2
	s_setprio 1
	s_waitcnt lgkmcnt(0)
	v_mfma_f32_16x16x32_bf16 v[60:63], v[150:153], v[182:185], v[60:63]
	v_mfma_f32_16x16x32_bf16 v[56:59], v[158:161], v[182:185], v[56:59]
	v_mfma_f32_16x16x32_bf16 v[44:47], v[150:153], v[190:193], v[44:47]
	v_mfma_f32_16x16x32_bf16 v[40:43], v[158:161], v[190:193], v[40:43]
	v_mfma_f32_16x16x32_bf16 v[28:31], v[150:153], v[198:201], v[28:31]
	v_mfma_f32_16x16x32_bf16 v[24:27], v[158:161], v[198:201], v[24:27]
	v_mfma_f32_16x16x32_bf16 v[12:15], v[150:153], v[206:209], v[12:15]
	v_mfma_f32_16x16x32_bf16 v[8:11], v[158:161], v[206:209], v[8:11]
	v_mfma_f32_16x16x32_bf16 v[52:55], v[166:169], v[182:185], v[52:55]
	v_mfma_f32_16x16x32_bf16 v[48:51], v[174:177], v[182:185], v[48:51]
	v_mfma_f32_16x16x32_bf16 v[36:39], v[166:169], v[190:193], v[36:39]
	v_mfma_f32_16x16x32_bf16 v[32:35], v[174:177], v[190:193], v[32:35]
	v_mfma_f32_16x16x32_bf16 v[20:23], v[166:169], v[198:201], v[20:23]
	v_mfma_f32_16x16x32_bf16 v[16:19], v[174:177], v[198:201], v[16:19]
	v_mfma_f32_16x16x32_bf16 v[4:7], v[166:169], v[206:209], v[4:7]
	v_mfma_f32_16x16x32_bf16 v[0:3], v[174:177], v[206:209], v[0:3]
	v_mfma_f32_16x16x32_bf16 v[60:63], v[154:157], v[186:189], v[60:63]
	v_mfma_f32_16x16x32_bf16 v[56:59], v[162:165], v[186:189], v[56:59]
	v_mfma_f32_16x16x32_bf16 v[44:47], v[154:157], v[194:197], v[44:47]
	v_mfma_f32_16x16x32_bf16 v[40:43], v[162:165], v[194:197], v[40:43]
	v_mfma_f32_16x16x32_bf16 v[28:31], v[154:157], v[202:205], v[28:31]
	v_mfma_f32_16x16x32_bf16 v[24:27], v[162:165], v[202:205], v[24:27]
	v_mfma_f32_16x16x32_bf16 v[12:15], v[154:157], v[210:213], v[12:15]
	v_mfma_f32_16x16x32_bf16 v[8:11], v[162:165], v[210:213], v[8:11]
	v_mfma_f32_16x16x32_bf16 v[52:55], v[170:173], v[186:189], v[52:55]
	v_mfma_f32_16x16x32_bf16 v[48:51], v[178:181], v[186:189], v[48:51]
	v_mfma_f32_16x16x32_bf16 v[36:39], v[170:173], v[194:197], v[36:39]
	v_mfma_f32_16x16x32_bf16 v[32:35], v[178:181], v[194:197], v[32:35]
	v_mfma_f32_16x16x32_bf16 v[20:23], v[170:173], v[202:205], v[20:23]
	v_mfma_f32_16x16x32_bf16 v[16:19], v[178:181], v[202:205], v[16:19]
	v_mfma_f32_16x16x32_bf16 v[4:7], v[170:173], v[210:213], v[4:7]
	v_mfma_f32_16x16x32_bf16 v[0:3], v[178:181], v[210:213], v[0:3]
	s_setprio 0
; #define PG8_STAGE(bufoff, gbase, voff) do { const char* _gb = (const char*)(gbase); asm volatile("" : "+s"(_gb));     \
;         _Pragma("unroll") for (int _i = 0; _i < 2; ++_i) \
;         __builtin_amdgcn_global_load_lds((const unsigned*)(_gb + (voff)[_i]), (LAS unsigned*)(lds + (bufoff) + ldsw + _i * 8192), 16, 0, 0); } while (0)
; #define PG8_LDA(dst, b, h) do { _Pragma("unroll") for (int m = 0; m < 4; ++m) _Pragma("unroll") for (int k = 0; k < 2; ++k) dst[m][k] = *(const LAS bf16x8*)(lds + PG8_SA(b, h) + aoff + m * 2048 + k * 1024); } while (0)
; #define PG8_LDB(dst, b, h) do { _Pragma("unroll") for (int n = 0; n < 2; ++n) _Pragma("unroll") for (int k = 0; k < 2; ++k) dst[n][k] = *(const LAS bf16x8*)(lds + PG8_SB(b, h) + boff + n * 2048 + k * 1024); } while (0)
; #define PG8_WAIT_V(n) asm volatile("s_waitcnt vmcnt(" #n ")" ::: "memory")
; #define PG8_WAIT_L(n) asm volatile("s_waitcnt lgkmcnt(" #n ")" ::: "memory")
; #define PG8_BAR __builtin_amdgcn_s_barrier()
; #define PG8_SCHED __builtin_amdgcn_sched_barrier(0)
; template <class Epi>
; __device__ __forceinline__ void gemm_phase(LAS unsigned char* lds, const Gemm g, const StaticOrder& S, const Epi& E) {
;     ...
;             PG8_LDB(B0, 1, 0); PG8_LDB(B1, 1, 1); PG8_SCHED; PG8_LDA(At, 1, 0); PG8_STAGE(PG8_SA(0, 1), a2 + hstepA, voffA);
;             PG8_WAIT_V(8); PG8_WAIT_L(0); PG8_BAR; PG8_MMA2(0, At, B0, B1); PG8_BAR; PG8_SCHED;
;             PG8_LDA(At, 1, 1); PG8_STAGE(PG8_SB(1, 0), b3, voffB); PG8_STAGE(PG8_SB(1, 1), b3 + hstepB, voffB); PG8_STAGE(PG8_SA(1, 0), a3, voffA);
;             PG8_WAIT_V(8); PG8_WAIT_L(0); PG8_BAR; PG8_MMA2(1, At, B0, B1); PG8_BAR; PG8_SCHED;
.Lp6_skipm2:
	s_barrier
	s_add_i32 s70, 0, 0x18000
	v_add_u32_e32 v132, s70, v131
	s_add_i32 s71, 0, 0x1c000
	ds_read_b128 v[150:153], v132
	ds_read_b128 v[154:157], v132 offset:1024
	ds_read_b128 v[158:161], v132 offset:2048
	ds_read_b128 v[162:165], v132 offset:3072
	v_add_u32_e32 v132, s71, v131
	ds_read_b128 v[166:169], v132
	ds_read_b128 v[170:173], v132 offset:1024
	ds_read_b128 v[174:177], v132 offset:2048
	ds_read_b128 v[178:181], v132 offset:3072
	s_add_u32 s54, s54, s22
	s_addc_u32 s55, s55, s23
	s_mov_b32 m0, s18
	ds_read_b128 v[182:185], v145 offset:32768
	ds_read_b128 v[186:189], v145 offset:33792
	ds_read_b128 v[190:193], v145 offset:34816
	ds_read_b128 v[194:197], v145 offset:35840
	ds_read_b128 v[198:201], v145 offset:36864
	ds_read_b128 v[202:205], v145 offset:37888
	ds_read_b128 v[206:209], v145 offset:38912
	ds_read_b128 v[210:213], v145 offset:39936
	s_nop 0
	global_load_lds_dwordx4 v134, s[54:55]
	s_mov_b32 m0, s19
	s_nop 0
	global_load_lds_dwordx4 v130, s[54:55]
	s_waitcnt vmcnt(8)
	s_waitcnt lgkmcnt(0)
	s_barrier
	s_cmp_eq_u32 s94, 2
	s_cbranch_scc1 .Lp6_skipm3
	s_setprio 1
	s_waitcnt lgkmcnt(0)
	v_mfma_f32_16x16x32_bf16 v[124:127], v[150:153], v[182:185], v[124:127]
	v_mfma_f32_16x16x32_bf16 v[120:123], v[158:161], v[182:185], v[120:123]
	v_mfma_f32_16x16x32_bf16 v[108:111], v[150:153], v[190:193], v[108:111]
	v_mfma_f32_16x16x32_bf16 v[104:107], v[158:161], v[190:193], v[104:107]
	v_mfma_f32_16x16x32_bf16 v[92:95], v[150:153], v[198:201], v[92:95]
	v_mfma_f32_16x16x32_bf16 v[88:91], v[158:161], v[198:201], v[88:91]
	v_mfma_f32_16x16x32_bf16 v[76:79], v[150:153], v[206:209], v[76:79]
	v_mfma_f32_16x16x32_bf16 v[72:75], v[158:161], v[206:209], v[72:75]
	v_mfma_f32_16x16x32_bf16 v[116:119], v[166:169], v[182:185], v[116:119]
	v_mfma_f32_16x16x32_bf16 v[112:115], v[174:177], v[182:185], v[112:115]
	v_mfma_f32_16x16x32_bf16 v[100:103], v[166:169], v[190:193], v[100:103]
	v_mfma_f32_16x16x32_bf16 v[96:99], v[174:177], v[190:193], v[96:99]
	v_mfma_f32_16x16x32_bf16 v[84:87], v[166:169], v[198:201], v[84:87]
	v_mfma_f32_16x16x32_bf16 v[80:83], v[174:177], v[198:201], v[80:83]
	v_mfma_f32_16x16x32_bf16 v[68:71], v[166:169], v[206:209], v[68:71]
	v_mfma_f32_16x16x32_bf16 v[64:67], v[174:177], v[206:209], v[64:67]
	v_mfma_f32_16x16x32_bf16 v[124:127], v[154:157], v[186:189], v[124:127]
	v_mfma_f32_16x16x32_bf16 v[120:123], v[162:165], v[186:189], v[120:123]
	v_mfma_f32_16x16x32_bf16 v[108:111], v[154:157], v[194:197], v[108:111]
	v_mfma_f32_16x16x32_bf16 v[104:107], v[162:165], v[194:197], v[104:107]
	v_mfma_f32_16x16x32_bf16 v[92:95], v[154:157], v[202:205], v[92:95]
	v_mfma_f32_16x16x32_bf16 v[88:91], v[162:165], v[202:205], v[88:91]
	v_mfma_f32_16x16x32_bf16 v[76:79], v[154:157], v[210:213], v[76:79]
	v_mfma_f32_16x16x32_bf16 v[72:75], v[162:165], v[210:213], v[72:75]
	v_mfma_f32_16x16x32_bf16 v[116:119], v[170:173], v[186:189], v[116:119]
	v_mfma_f32_16x16x32_bf16 v[112:115], v[178:181], v[186:189], v[112:115]
	v_mfma_f32_16x16x32_bf16 v[100:103], v[170:173], v[194:197], v[100:103]
	v_mfma_f32_16x16x32_bf16 v[96:99], v[178:181], v[194:197], v[96:99]
	v_mfma_f32_16x16x32_bf16 v[84:87], v[170:173], v[202:205], v[84:87]
	v_mfma_f32_16x16x32_bf16 v[80:83], v[178:181], v[202:205], v[80:83]
	v_mfma_f32_16x16x32_bf16 v[68:71], v[170:173], v[210:213], v[68:71]
	v_mfma_f32_16x16x32_bf16 v[64:67], v[178:181], v[210:213], v[64:67]
	s_setprio 0
.Lp6_skipm3:
	s_barrier
	s_add_u32 s52, s52, 0x80
	s_addc_u32 s53, s53, 0
	s_add_i32 s54, s70, s3
	s_mov_b32 m0, s54
	ds_read_b128 v[182:185], v145 offset:49152
	ds_read_b128 v[186:189], v145 offset:50176
	ds_read_b128 v[190:193], v145 offset:51200
	ds_read_b128 v[194:197], v145 offset:52224
	ds_read_b128 v[198:201], v145 offset:53248
	ds_read_b128 v[202:205], v145 offset:54272
	ds_read_b128 v[206:209], v145 offset:55296
	ds_read_b128 v[210:213], v145 offset:56320
	s_nop 0
	global_load_lds_dwordx4 v149, s[52:53]
	s_add_i32 m0, s54, 0x2000
	s_nop 0
	global_load_lds_dwordx4 v128, s[52:53]
	s_add_u32 s52, s56, 0x80
	s_addc_u32 s53, s57, 0
	s_add_i32 s54, s71, s3
	s_mov_b32 m0, s54
	s_nop 0
	global_load_lds_dwordx4 v149, s[52:53]
	s_add_i32 m0, s54, 0x2000
	s_nop 0
	global_load_lds_dwordx4 v128, s[52:53]
	s_mov_b32 m0, s33
	s_nop 0
	global_load_lds_dwordx4 v134, s[10:11]
	s_mov_b32 m0, s43
	s_nop 0
	global_load_lds_dwordx4 v130, s[10:11]
	s_waitcnt vmcnt(8)
	s_waitcnt lgkmcnt(0)
	s_barrier
	s_cmp_eq_u32 s94, 1
	s_cbranch_scc1 .Lp6_skipm4
	s_setprio 1
	s_waitcnt lgkmcnt(0)
	v_mfma_f32_16x16x32_bf16 v[60:63], v[150:153], v[182:185], v[60:63]
	v_mfma_f32_16x16x32_bf16 v[56:59], v[158:161], v[182:185], v[56:59]
	v_mfma_f32_16x16x32_bf16 v[44:47], v[150:153], v[190:193], v[44:47]
	v_mfma_f32_16x16x32_bf16 v[40:43], v[158:161], v[190:193], v[40:43]
	v_mfma_f32_16x16x32_bf16 v[28:31], v[150:153], v[198:201], v[28:31]
	v_mfma_f32_16x16x32_bf16 v[24:27], v[158:161], v[198:201], v[24:27]
	v_mfma_f32_16x16x32_bf16 v[12:15], v[150:153], v[206:209], v[12:15]
	v_mfma_f32_16x16x32_bf16 v[8:11], v[158:161], v[206:209], v[8:11]
	v_mfma_f32_16x16x32_bf16 v[52:55], v[166:169], v[182:185], v[52:55]
	v_mfma_f32_16x16x32_bf16 v[48:51], v[174:177], v[182:185], v[48:51]
	v_mfma_f32_16x16x32_bf16 v[36:39], v[166:169], v[190:193], v[36:39]
	v_mfma_f32_16x16x32_bf16 v[32:35], v[174:177], v[190:193], v[32:35]
	v_mfma_f32_16x16x32_bf16 v[20:23], v[166:169], v[198:201], v[20:23]
	v_mfma_f32_16x16x32_bf16 v[16:19], v[174:177], v[198:201], v[16:19]
	v_mfma_f32_16x16x32_bf16 v[4:7], v[166:169], v[206:209], v[4:7]
	v_mfma_f32_16x16x32_bf16 v[0:3], v[174:177], v[206:209], v[0:3]
	v_mfma_f32_16x16x32_bf16 v[60:63], v[154:157], v[186:189], v[60:63]
	v_mfma_f32_16x16x32_bf16 v[56:59], v[162:165], v[186:189], v[56:59]
	v_mfma_f32_16x16x32_bf16 v[44:47], v[154:157], v[194:197], v[44:47]
	v_mfma_f32_16x16x32_bf16 v[40:43], v[162:165], v[194:197], v[40:43]
	v_mfma_f32_16x16x32_bf16 v[28:31], v[154:157], v[202:205], v[28:31]
	v_mfma_f32_16x16x32_bf16 v[24:27], v[162:165], v[202:205], v[24:27]
	v_mfma_f32_16x16x32_bf16 v[12:15], v[154:157], v[210:213], v[12:15]
	v_mfma_f32_16x16x32_bf16 v[8:11], v[162:165], v[210:213], v[8:11]
	v_mfma_f32_16x16x32_bf16 v[52:55], v[170:173], v[186:189], v[52:55]
	v_mfma_f32_16x16x32_bf16 v[48:51], v[178:181], v[186:189], v[48:51]
	v_mfma_f32_16x16x32_bf16 v[36:39], v[170:173], v[194:197], v[36:39]
	v_mfma_f32_16x16x32_bf16 v[32:35], v[178:181], v[194:197], v[32:35]
	v_mfma_f32_16x16x32_bf16 v[20:23], v[170:173], v[202:205], v[20:23]
	v_mfma_f32_16x16x32_bf16 v[16:19], v[178:181], v[202:205], v[16:19]
	v_mfma_f32_16x16x32_bf16 v[4:7], v[170:173], v[210:213], v[4:7]
	v_mfma_f32_16x16x32_bf16 v[0:3], v[178:181], v[210:213], v[0:3]
	s_setprio 0
; __device__ __forceinline__ unsigned pk2(float lo, float hi) { unsigned r; asm volatile("v_cvt_pk_bf16_f32 %0, %1, %2" : "=v"(r) : "v"(lo), "v"(hi)); return r; }
;     __device__ __forceinline__ void operator()(const f32x4 (&acc)[2][2][4][2], const Unit& u, int wr, int wc, int fr, int fq) const {
;     ...
;         for (int i = 0; i < 8; ++i) rsv[i] = ss[row0 + (i >> 2) * HALF + (i & 3) * 16];
; #pragma unroll
;         for (int i = 0; i < 8; ++i) rsv[i] = __builtin_amdgcn_rsqf(rsv[i] * (1.0f / D) + EPS);
;         __builtin_amdgcn_sched_barrier(0);
; #pragma unroll
;         for (int ai = 0; ai < 2; ++ai)
; #pragma unroll
;             for (int m = 0; m < 4; ++m) {
;                 const int row = row0 + ai * HALF + m * 16;
;                 const float rs = rsv[ai * 4 + m];
;                 const f32x4 g0 = acc[ai][0][m][0], g1 = acc[ai][0][m][1], u0 = acc[ai][1][m][0], u1 = acc[ai][1][m][1];
;                 const f32x2 o0 = swiglu_pk((f32x2){g0[0], g0[1]}, (f32x2){u0[0], u0[1]}, rs), o1 = swiglu_pk((f32x2){g0[2], g0[3]}, (f32x2){u0[2], u0[3]}, rs);
;                 const f32x2 o2 = swiglu_pk((f32x2){g1[0], g1[1]}, (f32x2){u1[0], u1[1]}, rs), o3 = swiglu_pk((f32x2){g1[2], g1[3]}, (f32x2){u1[2], u1[3]}, rs);
;                 u32x4 w; w.x = pk2(o0.x, o0.y); w.y = pk2(o1.x, o1.y); w.z = pk2(o2.x, o2.y); w.w = pk2(o3.x, o3.y);
;                 __builtin_nontemporal_store(w, (u32x4*)(G + (size_t)(row >> 8) * ((size_t)BM * FF) + (size_t)(col0 >> 6) * (BM * BK) + (size_t)(row & 255) * BK + (col0 & 63)));
.Lp6_skipm4:
	s_barrier
	s_add_i32 s69, s69, 2
	s_add_u32 s65, s65, 0x100
	s_addc_u32 s66, s66, 0
	s_add_u32 s67, s67, 0x100
	s_addc_u32 s68, s68, 0
	s_cmp_gt_u32 s69, 29
	s_cbranch_scc0 .LBB0_1207
	s_and_b64 vcc, exec, s[40:41]
	s_cbranch_vccz .LBB0_1210
	s_barrier
.LBB0_1210:
	s_lshl_b32 s10, s50, 8
	s_add_i32 s45, s10, s26
	v_or_b32_e32 v154, s45, v129
	v_ashrrev_i32_e32 v155, 31, v154
	v_lshl_add_u64 v[150:151], v[154:155], 2, s[38:39]
	global_load_dword v132, v[150:151], off
	global_load_dword v141, v[150:151], off offset:64
	global_load_dword v142, v[150:151], off offset:128
	global_load_dword v144, v[150:151], off offset:192
	global_load_dword v146, v[150:151], off offset:512
	global_load_dword v148, v[150:151], off offset:576
	global_load_dword v152, v[150:151], off offset:640
	s_nop 0
	global_load_dword v150, v[150:151], off offset:704
	s_lshl_b32 s10, s63, 7
	s_or_b32 s10, s10, s27
	s_waitcnt vmcnt(0)
	v_fmamk_f32 v132, v132, 0x3a000000, v147
	v_fmamk_f32 v141, v141, 0x3a000000, v147
	v_fmamk_f32 v142, v142, 0x3a000000, v147
	v_fmamk_f32 v144, v144, 0x3a000000, v147
	v_fmamk_f32 v146, v146, 0x3a000000, v147
	v_fmamk_f32 v151, v148, 0x3a000000, v147
	v_fmamk_f32 v153, v152, 0x3a000000, v147
	v_fmamk_f32 v155, v150, 0x3a000000, v147
	v_rsq_f32_e32 v132, v132
	v_rsq_f32_e32 v156, v141
	v_rsq_f32_e32 v152, v142
	v_rsq_f32_e32 v150, v144
	v_rsq_f32_e32 v148, v146
	v_rsq_f32_e32 v146, v151
	v_rsq_f32_e32 v144, v153
	v_rsq_f32_e32 v142, v155
	v_add_u32_e32 v151, 0x80, v154
	v_pk_mul_f32 v[124:125], v[124:125], v[132:133] op_sel_hi:[1,0]
	v_pk_mul_f32 v[126:127], v[126:127], v[132:133] op_sel_hi:[1,0]
	v_pk_mul_f32 v[158:159], v[124:125], s[42:43] op_sel_hi:[1,0]
	v_pk_mul_f32 v[160:161], v[126:127], s[42:43] op_sel_hi:[1,0]
	v_exp_f32_e32 v158, v158
	v_exp_f32_e32 v159, v159
	v_exp_f32_e32 v160, v160
	v_exp_f32_e32 v161, v161
	v_pk_mul_f32 v[116:117], v[116:117], v[132:133] op_sel_hi:[1,0]
	v_pk_add_f32 v[158:159], v[158:159], 1.0 op_sel_hi:[1,0]
	v_pk_mul_f32 v[118:119], v[118:119], v[132:133] op_sel_hi:[1,0]
	v_rcp_f32_e32 v158, v158
	v_rcp_f32_e32 v159, v159
	v_pk_add_f32 v[160:161], v[160:161], 1.0 op_sel_hi:[1,0]
	v_pk_mul_f32 v[120:121], v[120:121], v[132:133] op_sel_hi:[1,0]
	v_rcp_f32_e32 v160, v160
	v_rcp_f32_e32 v161, v161
	v_pk_mul_f32 v[124:125], v[124:125], v[158:159]
	v_pk_mul_f32 v[122:123], v[122:123], v[132:133] op_sel_hi:[1,0]
	v_pk_mul_f32 v[116:117], v[116:117], v[124:125]
	v_pk_mul_f32 v[124:125], v[126:127], v[160:161]
	v_pk_mul_f32 v[126:127], v[122:123], s[42:43] op_sel_hi:[1,0]
	v_pk_mul_f32 v[118:119], v[118:119], v[124:125]
	v_pk_mul_f32 v[124:125], v[120:121], s[42:43] op_sel_hi:[1,0]
	v_exp_f32_e32 v126, v126
	v_exp_f32_e32 v124, v124
	v_exp_f32_e32 v125, v125
	v_exp_f32_e32 v127, v127
	s_ashr_i32 s10, s10, 6
	s_ashr_i32 s11, s10, 31
	v_pk_add_f32 v[124:125], v[124:125], 1.0 op_sel_hi:[1,0]
	v_pk_add_f32 v[126:127], v[126:127], 1.0 op_sel_hi:[1,0]
	v_rcp_f32_e32 v124, v124
	v_rcp_f32_e32 v125, v125
	v_rcp_f32_e32 v126, v126
	v_rcp_f32_e32 v127, v127
	s_ashr_i32 s45, s45, 8
	s_lshl_b64 s[10:11], s[10:11], 15
	s_mul_hi_i32 s50, s45, 0x2c0000
	s_mul_i32 s45, s45, 0x2c0000
	v_pk_mul_f32 v[120:121], v[120:121], v[124:125]
	v_pk_mul_f32 v[112:113], v[112:113], v[132:133] op_sel_hi:[1,0]
	s_add_u32 s45, s36, s45
	v_pk_mul_f32 v[120:121], v[112:113], v[120:121]
	v_pk_mul_f32 v[112:113], v[122:123], v[126:127]
	v_pk_mul_f32 v[114:115], v[114:115], v[132:133] op_sel_hi:[1,0]
	s_addc_u32 s50, s37, s50
	v_pk_mul_f32 v[122:123], v[114:115], v[112:113]
	v_cvt_pk_bf16_f32 v112, v116, v117
	s_add_u32 s52, s45, s10
	v_lshlrev_b32_e32 v116, 7, v154
	s_addc_u32 s53, s50, s11
	v_and_b32_e32 v132, 0x6780, v116
	v_lshl_add_u64 v[116:117], s[52:53], 0, v[132:133]
	v_mov_b32_e32 v141, v133
	v_lshl_add_u64 v[116:117], v[116:117], 0, v[140:141]
	v_cvt_pk_bf16_f32 v113, v118, v119
	v_cvt_pk_bf16_f32 v114, v120, v121
	v_cvt_pk_bf16_f32 v115, v122, v123
	s_cmp_eq_u32 s94, 2
	s_cbranch_scc1 .Lp6_nost0
	global_store_dwordx4 v[116:117], v[112:115], off nt
.Lp6_nost0:
	v_pk_mul_f32 v[108:109], v[108:109], v[156:157] op_sel_hi:[1,0]
	v_pk_mul_f32 v[110:111], v[110:111], v[156:157] op_sel_hi:[1,0]
	v_pk_mul_f32 v[112:113], v[108:109], s[42:43] op_sel_hi:[1,0]
	v_pk_mul_f32 v[114:115], v[110:111], s[42:43] op_sel_hi:[1,0]
	v_exp_f32_e32 v112, v112
	v_exp_f32_e32 v113, v113
	v_exp_f32_e32 v114, v114
	v_exp_f32_e32 v115, v115
	v_pk_mul_f32 v[100:101], v[100:101], v[156:157] op_sel_hi:[1,0]
	v_pk_add_f32 v[112:113], v[112:113], 1.0 op_sel_hi:[1,0]
	v_pk_mul_f32 v[102:103], v[102:103], v[156:157] op_sel_hi:[1,0]
	v_rcp_f32_e32 v112, v112
	v_rcp_f32_e32 v113, v113
	v_pk_add_f32 v[114:115], v[114:115], 1.0 op_sel_hi:[1,0]
	v_pk_mul_f32 v[104:105], v[104:105], v[156:157] op_sel_hi:[1,0]
	v_rcp_f32_e32 v114, v114
	v_rcp_f32_e32 v115, v115
	v_pk_mul_f32 v[108:109], v[108:109], v[112:113]
	v_pk_mul_f32 v[106:107], v[106:107], v[156:157] op_sel_hi:[1,0]
	v_pk_mul_f32 v[100:101], v[100:101], v[108:109]
	v_pk_mul_f32 v[108:109], v[110:111], v[114:115]
	v_pk_mul_f32 v[110:111], v[106:107], s[42:43] op_sel_hi:[1,0]
	v_pk_mul_f32 v[102:103], v[102:103], v[108:109]
	v_pk_mul_f32 v[108:109], v[104:105], s[42:43] op_sel_hi:[1,0]
	v_exp_f32_e32 v110, v110
	v_exp_f32_e32 v108, v108
	v_exp_f32_e32 v109, v109
	v_exp_f32_e32 v111, v111
	v_pk_mul_f32 v[96:97], v[96:97], v[156:157] op_sel_hi:[1,0]
	v_pk_mul_f32 v[98:99], v[98:99], v[156:157] op_sel_hi:[1,0]
	v_pk_add_f32 v[108:109], v[108:109], 1.0 op_sel_hi:[1,0]
	v_pk_add_f32 v[110:111], v[110:111], 1.0 op_sel_hi:[1,0]
	v_rcp_f32_e32 v108, v108
	v_rcp_f32_e32 v109, v109
	v_rcp_f32_e32 v110, v110
	v_rcp_f32_e32 v111, v111
	v_pk_mul_f32 v[104:105], v[104:105], v[108:109]
	s_nop 0
	v_pk_mul_f32 v[104:105], v[96:97], v[104:105]
	v_pk_mul_f32 v[96:97], v[106:107], v[110:111]
	s_nop 0
	v_pk_mul_f32 v[106:107], v[98:99], v[96:97]
	v_cvt_pk_bf16_f32 v96, v100, v101
	v_cvt_pk_bf16_f32 v97, v102, v103
	v_cvt_pk_bf16_f32 v98, v104, v105
	s_nop 0
	v_cvt_pk_bf16_f32 v99, v106, v107
	s_cmp_eq_u32 s94, 2
	s_cbranch_scc1 .Lp6_nost1
	global_store_dwordx4 v[116:117], v[96:99], off offset:2048 nt
; __device__ __forceinline__ unsigned pk2(float lo, float hi) { unsigned r; asm volatile("v_cvt_pk_bf16_f32 %0, %1, %2" : "=v"(r) : "v"(lo), "v"(hi)); return r; }
;     __device__ __forceinline__ void operator()(const f32x4 (&acc)[2][2][4][2], const Unit& u, int wr, int wc, int fr, int fq) const {
;     ...
;         for (int ai = 0; ai < 2; ++ai)
; #pragma unroll
;             for (int m = 0; m < 4; ++m) {
;                 const int row = row0 + ai * HALF + m * 16;
;                 const float rs = rsv[ai * 4 + m];
;                 const f32x4 g0 = acc[ai][0][m][0], g1 = acc[ai][0][m][1], u0 = acc[ai][1][m][0], u1 = acc[ai][1][m][1];
;                 const f32x2 o0 = swiglu_pk((f32x2){g0[0], g0[1]}, (f32x2){u0[0], u0[1]}, rs), o1 = swiglu_pk((f32x2){g0[2], g0[3]}, (f32x2){u0[2], u0[3]}, rs);
;                 const f32x2 o2 = swiglu_pk((f32x2){g1[0], g1[1]}, (f32x2){u1[0], u1[1]}, rs), o3 = swiglu_pk((f32x2){g1[2], g1[3]}, (f32x2){u1[2], u1[3]}, rs);
;                 u32x4 w; w.x = pk2(o0.x, o0.y); w.y = pk2(o1.x, o1.y); w.z = pk2(o2.x, o2.y); w.w = pk2(o3.x, o3.y);
;                 __builtin_nontemporal_store(w, (u32x4*)(G + (size_t)(row >> 8) * ((size_t)BM * FF) + (size_t)(col0 >> 6) * (BM * BK) + (size_t)(row & 255) * BK + (col0 & 63)));
.Lp6_nost1:
	v_pk_mul_f32 v[92:93], v[92:93], v[152:153] op_sel_hi:[1,0]
	v_pk_mul_f32 v[94:95], v[94:95], v[152:153] op_sel_hi:[1,0]
	v_pk_mul_f32 v[96:97], v[92:93], s[42:43] op_sel_hi:[1,0]
	v_pk_mul_f32 v[98:99], v[94:95], s[42:43] op_sel_hi:[1,0]
	v_exp_f32_e32 v96, v96
	v_exp_f32_e32 v97, v97
	v_exp_f32_e32 v98, v98
	v_exp_f32_e32 v99, v99
	v_pk_mul_f32 v[84:85], v[84:85], v[152:153] op_sel_hi:[1,0]
	v_pk_add_f32 v[96:97], v[96:97], 1.0 op_sel_hi:[1,0]
	v_pk_mul_f32 v[86:87], v[86:87], v[152:153] op_sel_hi:[1,0]
	v_rcp_f32_e32 v96, v96
	v_rcp_f32_e32 v97, v97
	v_pk_add_f32 v[98:99], v[98:99], 1.0 op_sel_hi:[1,0]
	v_pk_mul_f32 v[88:89], v[88:89], v[152:153] op_sel_hi:[1,0]
	v_rcp_f32_e32 v98, v98
	v_rcp_f32_e32 v99, v99
	v_pk_mul_f32 v[92:93], v[92:93], v[96:97]
	v_pk_mul_f32 v[90:91], v[90:91], v[152:153] op_sel_hi:[1,0]
	v_pk_mul_f32 v[84:85], v[84:85], v[92:93]
	v_pk_mul_f32 v[92:93], v[94:95], v[98:99]
	v_pk_mul_f32 v[94:95], v[90:91], s[42:43] op_sel_hi:[1,0]
	v_pk_mul_f32 v[86:87], v[86:87], v[92:93]
	v_pk_mul_f32 v[92:93], v[88:89], s[42:43] op_sel_hi:[1,0]
	v_exp_f32_e32 v94, v94
	v_exp_f32_e32 v92, v92
	v_exp_f32_e32 v93, v93
	v_exp_f32_e32 v95, v95
	v_pk_mul_f32 v[80:81], v[80:81], v[152:153] op_sel_hi:[1,0]
	v_pk_mul_f32 v[82:83], v[82:83], v[152:153] op_sel_hi:[1,0]
	v_pk_add_f32 v[92:93], v[92:93], 1.0 op_sel_hi:[1,0]
	v_pk_add_f32 v[94:95], v[94:95], 1.0 op_sel_hi:[1,0]
	v_rcp_f32_e32 v92, v92
	v_rcp_f32_e32 v93, v93
	v_rcp_f32_e32 v94, v94
	v_rcp_f32_e32 v95, v95
	v_pk_mul_f32 v[88:89], v[88:89], v[92:93]
	s_nop 0
	v_pk_mul_f32 v[88:89], v[80:81], v[88:89]
	v_pk_mul_f32 v[80:81], v[90:91], v[94:95]
	s_nop 0
	v_pk_mul_f32 v[90:91], v[82:83], v[80:81]
	v_cvt_pk_bf16_f32 v80, v84, v85
	v_add_co_u32_e32 v84, vcc, s61, v116
	v_cvt_pk_bf16_f32 v81, v86, v87
	v_cvt_pk_bf16_f32 v82, v88, v89
	v_cvt_pk_bf16_f32 v83, v90, v91
	s_nop 1
	v_addc_co_u32_e32 v85, vcc, 0, v117, vcc
	s_cmp_eq_u32 s94, 2
	s_cbranch_scc1 .Lp6_nost2
	global_store_dwordx4 v[84:85], v[80:83], off nt
.Lp6_nost2:
	v_pk_mul_f32 v[76:77], v[76:77], v[150:151] op_sel_hi:[1,0]
	v_pk_mul_f32 v[78:79], v[78:79], v[150:151] op_sel_hi:[1,0]
	v_pk_mul_f32 v[80:81], v[76:77], s[42:43] op_sel_hi:[1,0]
	v_pk_mul_f32 v[82:83], v[78:79], s[42:43] op_sel_hi:[1,0]
	v_exp_f32_e32 v80, v80
	v_exp_f32_e32 v81, v81
	v_exp_f32_e32 v82, v82
	v_exp_f32_e32 v83, v83
	v_pk_mul_f32 v[68:69], v[68:69], v[150:151] op_sel_hi:[1,0]
	v_pk_add_f32 v[80:81], v[80:81], 1.0 op_sel_hi:[1,0]
	v_pk_mul_f32 v[70:71], v[70:71], v[150:151] op_sel_hi:[1,0]
	v_rcp_f32_e32 v80, v80
	v_rcp_f32_e32 v81, v81
	v_pk_add_f32 v[82:83], v[82:83], 1.0 op_sel_hi:[1,0]
	v_pk_mul_f32 v[72:73], v[72:73], v[150:151] op_sel_hi:[1,0]
	v_rcp_f32_e32 v82, v82
	v_rcp_f32_e32 v83, v83
	v_pk_mul_f32 v[76:77], v[76:77], v[80:81]
	v_pk_mul_f32 v[74:75], v[74:75], v[150:151] op_sel_hi:[1,0]
	v_pk_mul_f32 v[68:69], v[68:69], v[76:77]
	v_pk_mul_f32 v[76:77], v[78:79], v[82:83]
	v_pk_mul_f32 v[78:79], v[74:75], s[42:43] op_sel_hi:[1,0]
	v_pk_mul_f32 v[70:71], v[70:71], v[76:77]
	v_pk_mul_f32 v[76:77], v[72:73], s[42:43] op_sel_hi:[1,0]
	v_exp_f32_e32 v78, v78
	v_exp_f32_e32 v76, v76
	v_exp_f32_e32 v77, v77
	v_exp_f32_e32 v79, v79
	v_pk_mul_f32 v[64:65], v[64:65], v[150:151] op_sel_hi:[1,0]
	v_pk_mul_f32 v[66:67], v[66:67], v[150:151] op_sel_hi:[1,0]
	v_pk_add_f32 v[76:77], v[76:77], 1.0 op_sel_hi:[1,0]
	v_pk_add_f32 v[78:79], v[78:79], 1.0 op_sel_hi:[1,0]
	v_rcp_f32_e32 v76, v76
	v_rcp_f32_e32 v77, v77
	v_rcp_f32_e32 v78, v78
	v_rcp_f32_e32 v79, v79
	v_pk_mul_f32 v[72:73], v[72:73], v[76:77]
	s_nop 0
	v_pk_mul_f32 v[72:73], v[64:65], v[72:73]
	v_pk_mul_f32 v[64:65], v[74:75], v[78:79]
	s_nop 0
	v_pk_mul_f32 v[74:75], v[66:67], v[64:65]
	v_cvt_pk_bf16_f32 v64, v68, v69
	v_cvt_pk_bf16_f32 v65, v70, v71
	v_cvt_pk_bf16_f32 v66, v72, v73
	s_nop 0
	v_cvt_pk_bf16_f32 v67, v74, v75
	s_cmp_eq_u32 s94, 2
	s_cbranch_scc1 .Lp6_nost3
	global_store_dwordx4 v[84:85], v[64:67], off offset:2048 nt
.Lp6_nost3:
	v_pk_mul_f32 v[60:61], v[60:61], v[148:149] op_sel_hi:[1,0]
	v_pk_mul_f32 v[62:63], v[62:63], v[148:149] op_sel_hi:[1,0]
	v_pk_mul_f32 v[66:67], v[60:61], s[42:43] op_sel_hi:[1,0]
	v_pk_mul_f32 v[68:69], v[62:63], s[42:43] op_sel_hi:[1,0]
	v_exp_f32_e32 v66, v66
	v_exp_f32_e32 v67, v67
	v_exp_f32_e32 v68, v68
	v_exp_f32_e32 v69, v69
	v_pk_mul_f32 v[52:53], v[52:53], v[148:149] op_sel_hi:[1,0]
	v_pk_add_f32 v[66:67], v[66:67], 1.0 op_sel_hi:[1,0]
	v_pk_mul_f32 v[54:55], v[54:55], v[148:149] op_sel_hi:[1,0]
	v_rcp_f32_e32 v66, v66
	v_rcp_f32_e32 v67, v67
	v_pk_add_f32 v[68:69], v[68:69], 1.0 op_sel_hi:[1,0]
	v_pk_mul_f32 v[56:57], v[56:57], v[148:149] op_sel_hi:[1,0]
	v_rcp_f32_e32 v68, v68
	v_rcp_f32_e32 v69, v69
	v_pk_mul_f32 v[60:61], v[60:61], v[66:67]
	v_pk_mul_f32 v[58:59], v[58:59], v[148:149] op_sel_hi:[1,0]
	v_pk_mul_f32 v[52:53], v[52:53], v[60:61]
	v_pk_mul_f32 v[60:61], v[62:63], v[68:69]
	v_pk_mul_f32 v[62:63], v[58:59], s[42:43] op_sel_hi:[1,0]
	v_pk_mul_f32 v[54:55], v[54:55], v[60:61]
	v_pk_mul_f32 v[60:61], v[56:57], s[42:43] op_sel_hi:[1,0]
	v_exp_f32_e32 v62, v62
	v_exp_f32_e32 v60, v60
	v_exp_f32_e32 v61, v61
	v_exp_f32_e32 v63, v63
	v_lshrrev_b32_e32 v64, 8, v151
	v_pk_mul_f32 v[48:49], v[48:49], v[148:149] op_sel_hi:[1,0]
	v_pk_add_f32 v[60:61], v[60:61], 1.0 op_sel_hi:[1,0]
	v_pk_add_f32 v[62:63], v[62:63], 1.0 op_sel_hi:[1,0]
	v_rcp_f32_e32 v60, v60
	v_rcp_f32_e32 v61, v61
	v_rcp_f32_e32 v62, v62
	v_rcp_f32_e32 v63, v63
	v_mul_hi_i32_i24_e32 v65, 0x2c0000, v64
	v_pk_mul_f32 v[56:57], v[56:57], v[60:61]
	v_mul_i32_i24_e32 v64, 0x2c0000, v64
	v_pk_mul_f32 v[56:57], v[48:49], v[56:57]
	v_pk_mul_f32 v[48:49], v[58:59], v[62:63]
	v_pk_mul_f32 v[50:51], v[50:51], v[148:149] op_sel_hi:[1,0]
	s_nop 0
	v_pk_mul_f32 v[58:59], v[50:51], v[48:49]
	v_cvt_pk_bf16_f32 v48, v52, v53
	v_cvt_pk_bf16_f32 v49, v54, v55
	v_lshl_add_u64 v[52:53], s[36:37], 0, v[64:65]
	v_lshlrev_b32_e32 v54, 7, v151
	v_lshl_add_u64 v[52:53], v[52:53], 0, s[10:11]
	v_and_b32_e32 v132, 0x6780, v54
	v_lshl_add_u64 v[52:53], v[52:53], 0, v[132:133]
	v_lshl_add_u64 v[52:53], v[52:53], 0, v[140:141]
	v_cvt_pk_bf16_f32 v50, v56, v57
	v_cvt_pk_bf16_f32 v51, v58, v59
	s_cmp_eq_u32 s94, 1
	s_cbranch_scc1 .Lp6_nost4
	global_store_dwordx4 v[52:53], v[48:51], off nt
; __device__ __forceinline__ unsigned pk2(float lo, float hi) { unsigned r; asm volatile("v_cvt_pk_bf16_f32 %0, %1, %2" : "=v"(r) : "v"(lo), "v"(hi)); return r; }
;     __device__ __forceinline__ void operator()(const f32x4 (&acc)[2][2][4][2], const Unit& u, int wr, int wc, int fr, int fq) const {
;     ...
;         for (int ai = 0; ai < 2; ++ai)
; #pragma unroll
;             for (int m = 0; m < 4; ++m) {
;                 const int row = row0 + ai * HALF + m * 16;
;                 const float rs = rsv[ai * 4 + m];
;                 const f32x4 g0 = acc[ai][0][m][0], g1 = acc[ai][0][m][1], u0 = acc[ai][1][m][0], u1 = acc[ai][1][m][1];
;                 const f32x2 o0 = swiglu_pk((f32x2){g0[0], g0[1]}, (f32x2){u0[0], u0[1]}, rs), o1 = swiglu_pk((f32x2){g0[2], g0[3]}, (f32x2){u0[2], u0[3]}, rs);
;                 const f32x2 o2 = swiglu_pk((f32x2){g1[0], g1[1]}, (f32x2){u1[0], u1[1]}, rs), o3 = swiglu_pk((f32x2){g1[2], g1[3]}, (f32x2){u1[2], u1[3]}, rs);
;                 u32x4 w; w.x = pk2(o0.x, o0.y); w.y = pk2(o1.x, o1.y); w.z = pk2(o2.x, o2.y); w.w = pk2(o3.x, o3.y);
;                 __builtin_nontemporal_store(w, (u32x4*)(G + (size_t)(row >> 8) * ((size_t)BM * FF) + (size_t)(col0 >> 6) * (BM * BK) + (size_t)(row & 255) * BK + (col0 & 63)));
.Lp6_nost4:
	v_pk_mul_f32 v[44:45], v[44:45], v[146:147] op_sel_hi:[1,0]
	v_pk_mul_f32 v[46:47], v[46:47], v[146:147] op_sel_hi:[1,0]
	v_pk_mul_f32 v[48:49], v[44:45], s[42:43] op_sel_hi:[1,0]
	v_pk_mul_f32 v[50:51], v[46:47], s[42:43] op_sel_hi:[1,0]
	v_exp_f32_e32 v48, v48
	v_exp_f32_e32 v49, v49
	v_exp_f32_e32 v50, v50
	v_exp_f32_e32 v51, v51
	v_pk_mul_f32 v[36:37], v[36:37], v[146:147] op_sel_hi:[1,0]
	v_pk_add_f32 v[48:49], v[48:49], 1.0 op_sel_hi:[1,0]
	v_pk_mul_f32 v[38:39], v[38:39], v[146:147] op_sel_hi:[1,0]
	v_rcp_f32_e32 v48, v48
	v_rcp_f32_e32 v49, v49
	v_pk_add_f32 v[50:51], v[50:51], 1.0 op_sel_hi:[1,0]
	v_pk_mul_f32 v[40:41], v[40:41], v[146:147] op_sel_hi:[1,0]
	v_rcp_f32_e32 v50, v50
	v_rcp_f32_e32 v51, v51
	v_pk_mul_f32 v[44:45], v[44:45], v[48:49]
	v_pk_mul_f32 v[42:43], v[42:43], v[146:147] op_sel_hi:[1,0]
	v_pk_mul_f32 v[36:37], v[36:37], v[44:45]
	v_pk_mul_f32 v[44:45], v[46:47], v[50:51]
	v_pk_mul_f32 v[46:47], v[42:43], s[42:43] op_sel_hi:[1,0]
	v_pk_mul_f32 v[38:39], v[38:39], v[44:45]
	v_pk_mul_f32 v[44:45], v[40:41], s[42:43] op_sel_hi:[1,0]
	v_exp_f32_e32 v46, v46
	v_exp_f32_e32 v44, v44
	v_exp_f32_e32 v45, v45
	v_exp_f32_e32 v47, v47
	v_pk_mul_f32 v[32:33], v[32:33], v[146:147] op_sel_hi:[1,0]
	v_pk_mul_f32 v[34:35], v[34:35], v[146:147] op_sel_hi:[1,0]
	v_pk_add_f32 v[44:45], v[44:45], 1.0 op_sel_hi:[1,0]
	v_pk_add_f32 v[46:47], v[46:47], 1.0 op_sel_hi:[1,0]
	v_rcp_f32_e32 v44, v44
	v_rcp_f32_e32 v45, v45
	v_rcp_f32_e32 v46, v46
	v_rcp_f32_e32 v47, v47
	v_pk_mul_f32 v[40:41], v[40:41], v[44:45]
	s_nop 0
	v_pk_mul_f32 v[40:41], v[32:33], v[40:41]
	v_pk_mul_f32 v[32:33], v[42:43], v[46:47]
	s_nop 0
	v_pk_mul_f32 v[42:43], v[34:35], v[32:33]
	v_cvt_pk_bf16_f32 v32, v36, v37
	v_cvt_pk_bf16_f32 v33, v38, v39
	v_cvt_pk_bf16_f32 v34, v40, v41
	s_nop 0
	v_cvt_pk_bf16_f32 v35, v42, v43
	s_cmp_eq_u32 s94, 1
	s_cbranch_scc1 .Lp6_nost5
	global_store_dwordx4 v[52:53], v[32:35], off offset:2048 nt
.Lp6_nost5:
	v_pk_mul_f32 v[28:29], v[28:29], v[144:145] op_sel_hi:[1,0]
	v_pk_mul_f32 v[30:31], v[30:31], v[144:145] op_sel_hi:[1,0]
	v_pk_mul_f32 v[32:33], v[28:29], s[42:43] op_sel_hi:[1,0]
	v_pk_mul_f32 v[34:35], v[30:31], s[42:43] op_sel_hi:[1,0]
	v_exp_f32_e32 v32, v32
	v_exp_f32_e32 v33, v33
	v_exp_f32_e32 v34, v34
	v_exp_f32_e32 v35, v35
	v_pk_mul_f32 v[20:21], v[20:21], v[144:145] op_sel_hi:[1,0]
	v_pk_add_f32 v[32:33], v[32:33], 1.0 op_sel_hi:[1,0]
	v_pk_mul_f32 v[22:23], v[22:23], v[144:145] op_sel_hi:[1,0]
	v_rcp_f32_e32 v32, v32
	v_rcp_f32_e32 v33, v33
	v_pk_add_f32 v[34:35], v[34:35], 1.0 op_sel_hi:[1,0]
	v_pk_mul_f32 v[24:25], v[24:25], v[144:145] op_sel_hi:[1,0]
	v_rcp_f32_e32 v34, v34
	v_rcp_f32_e32 v35, v35
	v_pk_mul_f32 v[28:29], v[28:29], v[32:33]
	v_pk_mul_f32 v[26:27], v[26:27], v[144:145] op_sel_hi:[1,0]
	v_pk_mul_f32 v[20:21], v[20:21], v[28:29]
	v_pk_mul_f32 v[28:29], v[30:31], v[34:35]
	v_pk_mul_f32 v[30:31], v[26:27], s[42:43] op_sel_hi:[1,0]
	v_pk_mul_f32 v[22:23], v[22:23], v[28:29]
	v_pk_mul_f32 v[28:29], v[24:25], s[42:43] op_sel_hi:[1,0]
	v_exp_f32_e32 v30, v30
	v_exp_f32_e32 v28, v28
	v_exp_f32_e32 v29, v29
	v_exp_f32_e32 v31, v31
	v_pk_mul_f32 v[16:17], v[16:17], v[144:145] op_sel_hi:[1,0]
	v_pk_mul_f32 v[18:19], v[18:19], v[144:145] op_sel_hi:[1,0]
	v_pk_add_f32 v[28:29], v[28:29], 1.0 op_sel_hi:[1,0]
	v_pk_add_f32 v[30:31], v[30:31], 1.0 op_sel_hi:[1,0]
	v_rcp_f32_e32 v28, v28
	v_rcp_f32_e32 v29, v29
	v_rcp_f32_e32 v30, v30
	v_rcp_f32_e32 v31, v31
	v_pk_mul_f32 v[24:25], v[24:25], v[28:29]
	s_nop 0
	v_pk_mul_f32 v[24:25], v[16:17], v[24:25]
	v_pk_mul_f32 v[16:17], v[26:27], v[30:31]
	s_nop 0
	v_pk_mul_f32 v[26:27], v[18:19], v[16:17]
	v_cvt_pk_bf16_f32 v16, v20, v21
	v_add_co_u32_e32 v20, vcc, s61, v52
	v_cvt_pk_bf16_f32 v17, v22, v23
	v_cvt_pk_bf16_f32 v18, v24, v25
	v_cvt_pk_bf16_f32 v19, v26, v27
	s_nop 1
	v_addc_co_u32_e32 v21, vcc, 0, v53, vcc
	s_cmp_eq_u32 s94, 1
	s_cbranch_scc1 .Lp6_nost6
	global_store_dwordx4 v[20:21], v[16:19], off nt
.Lp6_nost6:
	v_pk_mul_f32 v[12:13], v[12:13], v[142:143] op_sel_hi:[1,0]
	v_pk_mul_f32 v[14:15], v[14:15], v[142:143] op_sel_hi:[1,0]
	v_pk_mul_f32 v[16:17], v[12:13], s[42:43] op_sel_hi:[1,0]
	v_pk_mul_f32 v[18:19], v[14:15], s[42:43] op_sel_hi:[1,0]
	v_exp_f32_e32 v16, v16
	v_exp_f32_e32 v17, v17
	v_exp_f32_e32 v18, v18
	v_exp_f32_e32 v19, v19
	v_pk_mul_f32 v[4:5], v[4:5], v[142:143] op_sel_hi:[1,0]
	v_pk_add_f32 v[16:17], v[16:17], 1.0 op_sel_hi:[1,0]
	v_pk_mul_f32 v[6:7], v[6:7], v[142:143] op_sel_hi:[1,0]
	v_rcp_f32_e32 v16, v16
	v_rcp_f32_e32 v17, v17
	v_pk_add_f32 v[18:19], v[18:19], 1.0 op_sel_hi:[1,0]
	v_pk_mul_f32 v[8:9], v[8:9], v[142:143] op_sel_hi:[1,0]
	v_rcp_f32_e32 v18, v18
	v_rcp_f32_e32 v19, v19
	v_pk_mul_f32 v[12:13], v[12:13], v[16:17]
	v_pk_mul_f32 v[10:11], v[10:11], v[142:143] op_sel_hi:[1,0]
	v_pk_mul_f32 v[4:5], v[4:5], v[12:13]
	v_pk_mul_f32 v[12:13], v[14:15], v[18:19]
	v_pk_mul_f32 v[14:15], v[10:11], s[42:43] op_sel_hi:[1,0]
	v_pk_mul_f32 v[6:7], v[6:7], v[12:13]
	v_pk_mul_f32 v[12:13], v[8:9], s[42:43] op_sel_hi:[1,0]
	v_exp_f32_e32 v14, v14
	v_exp_f32_e32 v12, v12
	v_exp_f32_e32 v13, v13
	v_exp_f32_e32 v15, v15
	v_pk_mul_f32 v[0:1], v[0:1], v[142:143] op_sel_hi:[1,0]
	v_pk_mul_f32 v[2:3], v[2:3], v[142:143] op_sel_hi:[1,0]
	v_pk_add_f32 v[12:13], v[12:13], 1.0 op_sel_hi:[1,0]
	v_pk_add_f32 v[14:15], v[14:15], 1.0 op_sel_hi:[1,0]
	v_rcp_f32_e32 v12, v12
	v_rcp_f32_e32 v13, v13
	v_rcp_f32_e32 v14, v14
	v_rcp_f32_e32 v15, v15
	v_pk_mul_f32 v[8:9], v[8:9], v[12:13]
	s_nop 0
	v_pk_mul_f32 v[8:9], v[0:1], v[8:9]
	v_pk_mul_f32 v[0:1], v[10:11], v[14:15]
	s_nop 0
	v_pk_mul_f32 v[10:11], v[2:3], v[0:1]
	v_cvt_pk_bf16_f32 v0, v4, v5
	v_cvt_pk_bf16_f32 v1, v6, v7
	v_cvt_pk_bf16_f32 v2, v8, v9
	s_nop 0
	v_cvt_pk_bf16_f32 v3, v10, v11
	s_cmp_eq_u32 s94, 1
	s_cbranch_scc1 .Lp6_nost7
	global_store_dwordx4 v[20:21], v[0:3], off offset:2048 nt
.Lp6_nost7:
	s_and_b64 vcc, exec, s[8:9]
	s_mov_b64 s[8:9], -1
	s_cbranch_vccnz .LBB0_1201
	s_andn2_b64 vcc, exec, s[34:35]
	s_cbranch_vccnz .LBB0_1200
	s_barrier
	s_branch .LBB0_1200
